# combine loop: 8-lane sum exchanges by DPP moves instead of ds_bpermute round trips
# speedup vs baseline: 1.0006x; 1.0006x over previous
.LBB0_176:
	v_add_co_u32_e32 v28, vcc, 0xf9720000, v6
	v_add_u32_e32 v0, s0, v0
	s_nop 0
	v_addc_co_u32_e32 v29, vcc, -1, v7, vcc
	v_add_co_u32_e32 v14, vcc, 0x3b80000, v6
	global_load_dwordx4 v[10:13], v[28:29], off
	s_nop 0
	v_addc_co_u32_e32 v15, vcc, 0, v7, vcc
	global_load_dwordx4 v[14:17], v[14:15], off
	s_nop 0
	global_load_dwordx4 v[18:21], v[6:7], off
	v_cmp_lt_i32_e32 vcc, s35, v0
	v_lshl_add_u64 v[6:7], v[6:7], 0, s[76:77]
	s_or_b64 s[38:39], vcc, s[38:39]
	s_waitcnt vmcnt(0)
	v_lshlrev_b32_e32 v22, 16, v13
	v_and_b32_e32 v23, 0xffff0000, v13
	v_lshlrev_b32_e32 v24, 16, v17
	v_and_b32_e32 v25, 0xffff0000, v17
	v_pk_add_f32 v[32:33], v[22:23], v[24:25]
	v_lshlrev_b32_e32 v22, 16, v12
	v_and_b32_e32 v23, 0xffff0000, v12
	v_lshlrev_b32_e32 v12, 16, v16
	v_and_b32_e32 v13, 0xffff0000, v16
	v_lshlrev_b32_e32 v30, 16, v21
	v_and_b32_e32 v31, 0xffff0000, v21
	v_lshlrev_b32_e32 v16, 16, v20
	v_and_b32_e32 v17, 0xffff0000, v20
	v_pk_add_f32 v[12:13], v[22:23], v[12:13]
	global_load_dwordx4 v[20:23], v[4:5], off offset:16
	global_load_dwordx4 v[24:27], v[4:5], off
	v_mul_f32_e32 v1, 0xbfb8aa3b, v16
	v_exp_f32_e32 v1, v1
	v_lshlrev_b32_e32 v42, 16, v19
	v_and_b32_e32 v43, 0xffff0000, v19
	v_lshlrev_b32_e32 v40, 16, v15
	v_add_f32_e32 v1, 1.0, v1
	v_rcp_f32_e32 v38, v1
	v_mul_f32_e32 v1, 0xbfb8aa3b, v17
	v_exp_f32_e32 v1, v1
	v_and_b32_e32 v41, 0xffff0000, v15
	v_and_b32_e32 v15, 0xffff0000, v18
	v_pk_mul_f32 v[36:37], v[12:13], v[12:13]
	v_add_f32_e32 v1, 1.0, v1
	v_rcp_f32_e32 v39, v1
	v_mul_f32_e32 v1, 0xbfb8aa3b, v42
	v_exp_f32_e32 v1, v1
	v_pk_mul_f32 v[34:35], v[32:33], v[32:33]
	v_pk_mul_f32 v[16:17], v[38:39], v[16:17]
	v_lshlrev_b32_e32 v38, 16, v11
	v_add_f32_e32 v1, 1.0, v1
	v_rcp_f32_e32 v44, v1
	v_mul_f32_e32 v1, 0xbfb8aa3b, v43
	v_exp_f32_e32 v1, v1
	v_and_b32_e32 v39, 0xffff0000, v11
	v_and_b32_e32 v11, 0xffff0000, v14
	v_pk_add_f32 v[38:39], v[38:39], v[40:41]
	v_add_f32_e32 v1, 1.0, v1
	v_rcp_f32_e32 v45, v1
	v_pk_mul_f32 v[40:41], v[38:39], v[38:39]
	v_pk_mul_f32 v[42:43], v[44:45], v[42:43]
	v_lshlrev_b32_e32 v44, 16, v10
	v_and_b32_e32 v45, 0xffff0000, v10
	v_lshlrev_b32_e32 v10, 16, v14
	v_lshlrev_b32_e32 v14, 16, v18
	v_mul_f32_e32 v1, 0xbfb8aa3b, v14
	v_exp_f32_e32 v1, v1
	v_pk_add_f32 v[10:11], v[44:45], v[10:11]
	v_add_f32_e32 v1, 1.0, v1
	v_rcp_f32_e32 v44, v1
	v_mul_f32_e32 v1, 0xbfb8aa3b, v15
	v_exp_f32_e32 v1, v1
	v_pk_mul_f32 v[18:19], v[10:11], v[10:11]
	v_add_f32_e32 v1, 1.0, v1
	v_rcp_f32_e32 v45, v1
	v_add_f32_e32 v1, v18, v19
	v_add_f32_e32 v1, v40, v1
	v_add_f32_e32 v1, v41, v1
	v_add_f32_e32 v1, v36, v1
	v_add_f32_e32 v1, v37, v1
	v_add_f32_e32 v1, v34, v1
	v_add_f32_e32 v1, v35, v1
	s_nop 1
	v_mov_b32_dpp v18, v1 row_shl:4 row_mask:0xf bank_mask:0x5
	v_mov_b32_dpp v18, v1 row_shr:4 row_mask:0xf bank_mask:0xa
	v_pk_mul_f32 v[14:15], v[44:45], v[14:15]
	s_waitcnt lgkmcnt(0)
	v_add_f32_e32 v1, v1, v18
	s_nop 1
	v_mov_b32_dpp v18, v1 quad_perm:[2,3,0,1] row_mask:0xf bank_mask:0xf
	s_waitcnt lgkmcnt(0)
	v_add_f32_e32 v1, v1, v18
	s_nop 1
	v_mov_b32_dpp v18, v1 quad_perm:[1,0,3,2] row_mask:0xf bank_mask:0xf
	s_waitcnt lgkmcnt(0)
	v_add_f32_e32 v1, v1, v18
	v_fmamk_f32 v1, v1, 0x3c800000, v174
	v_rsq_f32_e32 v18, v1
	v_mul_f32_e32 v1, 0xbfb8aa3b, v30
	v_exp_f32_e32 v1, v1
	v_pk_mul_f32 v[12:13], v[12:13], v[18:19] op_sel_hi:[1,0]
	s_waitcnt vmcnt(1)
	v_pk_mul_f32 v[12:13], v[20:21], v[12:13]
	v_add_f32_e32 v1, 1.0, v1
	v_pk_mul_f32 v[12:13], v[16:17], v[12:13]
	v_rcp_f32_e32 v16, v1
	v_mul_f32_e32 v1, 0xbfb8aa3b, v31
	v_exp_f32_e32 v1, v1
	v_pk_mul_f32 v[10:11], v[10:11], v[18:19] op_sel_hi:[1,0]
	v_cvt_pk_bf16_f32 v12, v12, v13
	s_waitcnt vmcnt(0)
	v_pk_mul_f32 v[10:11], v[24:25], v[10:11]
	v_add_f32_e32 v1, 1.0, v1
	v_rcp_f32_e32 v17, v1
	v_pk_mul_f32 v[10:11], v[14:15], v[10:11]
	v_pk_mul_f32 v[14:15], v[38:39], v[18:19] op_sel_hi:[1,0]
	v_pk_mul_f32 v[18:19], v[32:33], v[18:19] op_sel_hi:[1,0]
	v_pk_mul_f32 v[14:15], v[26:27], v[14:15]
	v_pk_mul_f32 v[18:19], v[22:23], v[18:19]
	v_pk_mul_f32 v[16:17], v[16:17], v[30:31]
	v_pk_mul_f32 v[14:15], v[42:43], v[14:15]
	v_pk_mul_f32 v[16:17], v[16:17], v[18:19]
	v_cvt_pk_bf16_f32 v10, v10, v11
	v_cvt_pk_bf16_f32 v11, v14, v15
	v_cvt_pk_bf16_f32 v13, v16, v17
	global_store_dwordx4 v[28:29], v[10:13], off
	s_andn2_b64 exec, exec, s[38:39]
	s_cbranch_execnz .LBB0_176
